# P4 attention: list entries of both wave tasks fetched during K/V staging, Q rows of second task + gathered first task prefetched after the staging barrier (dependent load chains broken)
# baseline (speedup 1.0000x reference)
; DI void attn_task(const Params& P, int bh, int n, int t, int lane, const char* Ks, const char* Vs) {
;     ...
;     const int cnt = gcount[bh * 32 + n], idx = (t - 8) * 32 + r;
;     valid = idx < cnt;
;     const int e = list[((long)(bh * 32 + n)) * 8192 + (valid ? idx : 0)];
; DI void phase4(const Params& P, char* smem) {
;     ...
;     while (hi - lo > 1) { const int mid = (lo + hi) >> 1; if (pre[mid] <= it) lo = mid; else hi = mid; }
;     const int bh = lo >> 5, n = lo & 31, b = bh >> 3, h = bh & 7;
;     const int ntask = 4 + ((gcount[lo] + 31) >> 5);
;     const int task = (it - pre[lo]) * 8 + wid;
;     uint4 kr[8], vr[8];
; #pragma unroll
;     for (int i = 0; i < 8; ++i) {
;       const int q = i * 256 + tid;
;       kr[i] = *reinterpret_cast<const uint4*>(Kb + ((long)(b * 8192 + n * 256 + (q >> 3))) * 512 + h * 64 + (q & 7) * 8);
;       vr[i] = *reinterpret_cast<const uint4*>(Vt + ((long)(bh * 64 + (q >> 5))) * 8192 + n * 256 + (q & 31) * 8);
;     }
; #pragma unroll
;     for (int i = 0; i < 8; ++i) {
;       const int q = i * 256 + tid, row = q >> 3;
;       *reinterpret_cast<uint4*>(Ks + row * 128 + (((q & 7) ^ ((row >> 1) & 7)) * 16)) = kr[i];
;       *reinterpret_cast<uint4*>(Vs + (q >> 5) * 528 + (q & 31) * 16) = vr[i];
;     }
;     __syncthreads();
.LBB0_769:
	v_add_u32_e32 v2, v0, v66
	v_ashrrev_i32_e32 v2, 1, v2
	v_lshl_add_u32 v3, v2, 2, v92
	ds_read_b32 v3, v3
	s_waitcnt lgkmcnt(0)
	v_cmp_gt_i32_e32 vcc, v3, v144
	s_nop 1
	v_cndmask_b32_e32 v0, v0, v2, vcc
	v_cndmask_b32_e32 v66, v2, v66, vcc
	v_sub_u32_e32 v2, v0, v66
	v_cmp_gt_i32_e32 vcc, 2, v2
	s_or_b64 s[0:1], vcc, s[0:1]
	s_andn2_b64 exec, exec, s[0:1]
	s_cbranch_execnz .LBB0_769
	s_or_b64 exec, exec, s[0:1]
	v_lshlrev_b32_e32 v0, 5, v66
	v_ashrrev_i32_e32 v74, 5, v66
	v_and_b32_e32 v16, 0xffffe000, v0
	v_lshlrev_b32_e32 v0, 8, v66
	v_and_b32_e32 v145, 0x1f00, v0
	v_lshlrev_b32_e32 v17, 6, v74
	v_lshlrev_b32_e32 v0, 7, v74
	v_and_b32_e32 v0, 0x380, v0
	v_or_b32_e32 v12, v17, v102
	v_lshl_add_u64 v[2:3], v[80:81], 0, v[0:1]
	v_lshlrev_b32_e32 v0, 1, v145
	v_ashrrev_i32_e32 v13, 31, v12
	v_lshl_add_u64 v[4:5], v[82:83], 0, v[0:1]
	v_lshlrev_b64 v[12:13], 14, v[12:13]
	v_lshl_add_u64 v[14:15], v[4:5], 0, v[12:13]
	v_or3_b32 v12, v16, v103, v145
	v_ashrrev_i32_e32 v13, 31, v12
	v_lshlrev_b64 v[12:13], 10, v[12:13]
	v_lshl_add_u64 v[18:19], v[2:3], 0, v[12:13]
	v_or_b32_e32 v12, v17, v104
	v_ashrrev_i32_e32 v13, 31, v12
	v_lshlrev_b64 v[12:13], 14, v[12:13]
	v_lshl_add_u64 v[22:23], v[4:5], 0, v[12:13]
	v_or3_b32 v12, v16, v105, v145
	v_ashrrev_i32_e32 v13, 31, v12
	v_lshlrev_b64 v[12:13], 10, v[12:13]
	v_lshl_add_u64 v[26:27], v[2:3], 0, v[12:13]
	v_or_b32_e32 v12, v17, v106
	v_ashrrev_i32_e32 v13, 31, v12
	v_lshlrev_b64 v[12:13], 14, v[12:13]
	v_lshl_add_u64 v[30:31], v[4:5], 0, v[12:13]
	v_or3_b32 v12, v16, v107, v145
	v_ashrrev_i32_e32 v13, 31, v12
	v_lshlrev_b64 v[12:13], 10, v[12:13]
	v_lshl_add_u64 v[34:35], v[2:3], 0, v[12:13]
	v_or_b32_e32 v12, v17, v108
	v_ashrrev_i32_e32 v13, 31, v12
	v_lshlrev_b64 v[12:13], 14, v[12:13]
	v_lshl_add_u64 v[38:39], v[4:5], 0, v[12:13]
	v_or3_b32 v12, v16, v109, v145
	v_ashrrev_i32_e32 v13, 31, v12
	v_lshlrev_b64 v[12:13], 10, v[12:13]
	v_lshl_add_u64 v[42:43], v[2:3], 0, v[12:13]
	v_or_b32_e32 v12, v17, v110
	v_ashrrev_i32_e32 v13, 31, v12
	v_lshlrev_b64 v[12:13], 14, v[12:13]
	v_lshl_add_u64 v[46:47], v[4:5], 0, v[12:13]
	v_or3_b32 v12, v16, v111, v145
	v_ashrrev_i32_e32 v13, 31, v12
	v_lshlrev_b64 v[12:13], 10, v[12:13]
	v_lshl_add_u64 v[50:51], v[2:3], 0, v[12:13]
	v_or_b32_e32 v12, v17, v112
	v_ashrrev_i32_e32 v13, 31, v12
	v_lshlrev_b64 v[12:13], 14, v[12:13]
	v_ashrrev_i32_e32 v67, 31, v66
	v_or3_b32 v6, v16, v175, v145
	v_or3_b32 v10, v16, v101, v145
	v_lshl_add_u64 v[54:55], v[4:5], 0, v[12:13]
	v_or3_b32 v12, v16, v113, v145
	v_lshl_add_u64 v[68:69], v[66:67], 2, s[28:29]
	v_ashrrev_i32_e32 v7, 31, v6
	v_ashrrev_i32_e32 v11, 31, v10
	v_ashrrev_i32_e32 v13, 31, v12
	global_load_dword v70, v[68:69], off
	v_lshlrev_b64 v[6:7], 10, v[6:7]
	v_lshlrev_b64 v[10:11], 10, v[10:11]
	v_lshlrev_b64 v[12:13], 10, v[12:13]
	v_lshl_add_u64 v[6:7], v[2:3], 0, v[6:7]
	v_or_b32_e32 v8, v17, v100
	v_lshl_add_u64 v[10:11], v[2:3], 0, v[10:11]
	v_lshl_add_u64 v[58:59], v[2:3], 0, v[12:13]
	v_or_b32_e32 v2, v17, v114
	v_ashrrev_i32_e32 v9, 31, v8
	v_ashrrev_i32_e32 v3, 31, v2
	v_lshlrev_b64 v[8:9], 14, v[8:9]
	v_lshlrev_b64 v[2:3], 14, v[2:3]
	v_lshl_add_u64 v[8:9], v[4:5], 0, v[8:9]
	v_lshl_add_u64 v[62:63], v[4:5], 0, v[2:3]
	global_load_dwordx4 v[2:5], v[6:7], off
	s_nop 0
	global_load_dwordx4 v[6:9], v[8:9], off
	s_nop 0
	global_load_dwordx4 v[10:13], v[10:11], off
	s_nop 0
	global_load_dwordx4 v[14:17], v[14:15], off
	s_nop 0
	global_load_dwordx4 v[18:21], v[18:19], off
	s_nop 0
	global_load_dwordx4 v[22:25], v[22:23], off
	s_nop 0
	global_load_dwordx4 v[26:29], v[26:27], off
	s_nop 0
	global_load_dwordx4 v[30:33], v[30:31], off
	s_nop 0
	global_load_dwordx4 v[34:37], v[34:35], off
	s_nop 0
	global_load_dwordx4 v[38:41], v[38:39], off
	s_nop 0
	global_load_dwordx4 v[42:45], v[42:43], off
	s_nop 0
	global_load_dwordx4 v[46:49], v[46:47], off
	s_nop 0
	global_load_dwordx4 v[50:53], v[50:51], off
	s_nop 0
	global_load_dwordx4 v[54:57], v[54:55], off
	s_nop 0
	global_load_dwordx4 v[58:61], v[58:59], off
	s_nop 0
	global_load_dwordx4 v[62:65], v[62:63], off
	v_lshl_add_u32 v0, v66, 2, v92
	ds_read_b32 v146, v0
	v_lshlrev_b64 v[250:251], 14, v[66:67]
	v_lshl_add_u64 v[250:251], s[30:31], 0, v[250:251]
	v_mov_b32_e32 v253, 0
	v_mov_b32_e32 v215, 0
	s_waitcnt vmcnt(16) lgkmcnt(0)
	v_mov_b32_e32 v212, v70
	v_sub_u32_e32 v213, v144, v146
	v_lshl_or_b32 v213, v213, 3, v194
	v_add_u32_e32 v252, 8, v213
	v_lshl_add_u32 v252, v252, 5, v98
	v_cmp_lt_i32_e64 s[26:27], v252, v70
	v_or_b32_e32 v214, 4, v213
	v_lshl_add_u32 v214, v214, 5, v98
	v_max_i32_e32 v214, 0, v214
	v_cndmask_b32_e64 v252, 0, v252, s[26:27]
	v_cmp_lt_i32_e64 s[26:27], v214, v70
	v_lshl_add_u64 v[252:253], v[252:253], 1, v[250:251]
	global_load_ushort v248, v[252:253], off
	s_nop 0
	v_cndmask_b32_e64 v214, 0, v214, s[26:27]
	v_lshl_add_u64 v[214:215], v[214:215], 1, v[250:251]
	global_load_ushort v249, v[214:215], off
	s_waitcnt vmcnt(17)
	ds_write_b128 v115, v[2:5]
	s_waitcnt vmcnt(16)
	ds_write_b128 v116, v[6:9]
	s_waitcnt vmcnt(15)
	ds_write_b128 v117, v[10:13]
	s_waitcnt vmcnt(14)
	ds_write_b128 v118, v[14:17]
	s_waitcnt vmcnt(13)
	ds_write_b128 v119, v[18:21]
	s_waitcnt vmcnt(12)
	ds_write_b128 v120, v[22:25]
	s_waitcnt vmcnt(11)
	ds_write_b128 v121, v[26:29]
	s_waitcnt vmcnt(10)
	ds_write_b128 v122, v[30:33]
	s_waitcnt vmcnt(9)
	ds_write_b128 v123, v[34:37]
	s_waitcnt vmcnt(8)
	ds_write_b128 v125, v[38:41]
	s_waitcnt vmcnt(7)
	ds_write_b128 v126, v[42:45]
	s_waitcnt vmcnt(6)
	ds_write_b128 v127, v[46:49]
	s_waitcnt vmcnt(5)
	ds_write_b128 v130, v[50:53]
	s_waitcnt vmcnt(4)
	ds_write_b128 v131, v[54:57]
	s_waitcnt vmcnt(3)
	ds_write_b128 v132, v[58:61]
	s_waitcnt vmcnt(2)
	ds_write_b128 v133, v[62:65]
	v_add_u32_e32 v0, 31, v70
	v_ashrrev_i32_e32 v77, 5, v0
	s_waitcnt lgkmcnt(14)
	v_sub_u32_e32 v76, v144, v146
	v_add_u32_e32 v0, 4, v77
	v_lshl_or_b32 v75, v76, 3, v194
	v_cmp_lt_i32_e32 vcc, v75, v0
	s_and_b64 s[0:1], s[6:7], vcc
	s_waitcnt lgkmcnt(0)
	s_barrier
; DI void attn_task(const Params& P, int bh, int n, int t, int lane, const char* Ks, const char* Vs) {
;     ...
;     const u16* qrow = Qb + ((long)(b * 8192 + lq)) * 512 + h * 64 + 8 * hh;
; #pragma unroll
;     for (int s = 0; s < 4; ++s) qf[s] = *reinterpret_cast<const bf16x8*>(qrow + 16 * s);
; DI void phase4(const Params& P, char* smem) {
;     ...
;     if (act && task < ntask) {
;       if (task < 4) { attn_task(P, bh, n, task, lane, Ks, Vs); attn_task(P, bh, n, 7 - task, lane, Ks, Vs); }
;       else attn_task(P, bh, n, task - 4 + 8, lane, Ks, Vs);
;     }
;     if (act && task + 4 < ntask) attn_task(P, bh, n, task + 4 - 4 + 8, lane, Ks, Vs);
	s_waitcnt vmcnt(1)
	v_lshrrev_b32_e32 v252, 2, v248
	v_lshlrev_b32_e32 v250, 10, v74
	v_and_b32_e32 v250, 0xffffe000, v250
	v_add_u32_e32 v250, v252, v250
	v_ashrrev_i32_e32 v251, 31, v250
	v_lshlrev_b64 v[250:251], 10, v[250:251]
	v_lshl_add_u64 v[250:251], s[78:79], 0, v[250:251]
	v_bfe_u32 v252, v66, 5, 3
	v_lshlrev_b32_e32 v252, 7, v252
	v_mov_b32_e32 v253, 0
	v_lshl_add_u64 v[250:251], v[250:251], 0, v[252:253]
	v_lshlrev_b32_e32 v252, 1, v84
	v_lshl_add_u64 v[250:251], v[250:251], 0, v[252:253]
	global_load_dwordx4 v[232:235], v[250:251], off
	global_load_dwordx4 v[236:239], v[250:251], off offset:32
	global_load_dwordx4 v[240:243], v[250:251], off offset:64
	global_load_dwordx4 v[244:247], v[250:251], off offset:96
	v_cmp_lt_i32_e32 vcc, 3, v75
	s_and_b64 vcc, vcc, s[0:1]
	s_cbranch_vccz .Lattn_noqa
	s_waitcnt vmcnt(4)
	v_lshrrev_b32_e32 v252, 2, v249
	v_lshlrev_b32_e32 v250, 10, v74
	v_and_b32_e32 v250, 0xffffe000, v250
	v_add_u32_e32 v250, v252, v250
	v_ashrrev_i32_e32 v251, 31, v250
	v_lshlrev_b64 v[250:251], 10, v[250:251]
	v_lshl_add_u64 v[250:251], s[78:79], 0, v[250:251]
	v_bfe_u32 v252, v66, 5, 3
	v_lshlrev_b32_e32 v252, 7, v252
	v_mov_b32_e32 v253, 0
	v_lshl_add_u64 v[250:251], v[250:251], 0, v[252:253]
	v_lshlrev_b32_e32 v252, 1, v84
	v_lshl_add_u64 v[250:251], v[250:251], 0, v[252:253]
	global_load_dwordx4 v[50:53], v[250:251], off
	global_load_dwordx4 v[54:57], v[250:251], off offset:32
	global_load_dwordx4 v[58:61], v[250:251], off offset:64
	global_load_dwordx4 v[62:65], v[250:251], off offset:96
.Lattn_noqa:
	s_and_saveexec_b64 s[48:49], s[0:1]
	s_cbranch_execz .LBB0_775
	v_cmp_lt_i32_e32 vcc, 3, v75
	s_mov_b64 s[50:51], 0
	s_and_saveexec_b64 s[0:1], vcc
	s_xor_b64 s[24:25], exec, s[0:1]
	s_cbranch_execnz .LBB0_785
	s_andn2_saveexec_b64 s[56:57], s[24:25]
	s_cbranch_execnz .LBB0_801

; DI void attn_task(const Params& P, int bh, int n, int t, int lane, const char* Ks, const char* Vs) {
;     ...
;   int lq, slot; bool valid = true;
;   if (own) { lq = n * 256 + t * 32 + r; slot = 3; }
;   else {
;     const int cnt = gcount[bh * 32 + n], idx = (t - 8) * 32 + r;
;     valid = idx < cnt;
;     const int e = list[((long)(bh * 32 + n)) * 8192 + (valid ? idx : 0)];
;     lq = e >> 2; slot = e & 3;
;   }
;   bf16x8 qf[4];
;   {
;     const u16* qrow = Qb + ((long)(b * 8192 + lq)) * 512 + h * 64 + 8 * hh;
; #pragma unroll
;     for (int s = 0; s < 4; ++s) qf[s] = *reinterpret_cast<const bf16x8*>(qrow + 16 * s);
;   }
;   float m_run = -1e30f, l_run = 0.f;
;   f32x16 O0, O1;
; #pragma unroll
;   for (int i = 0; i < 16; ++i) { O0[i] = 0.f; O1[i] = 0.f; }
;   const int nkt = own ? (t + 1) : 8;
.LBB0_775:
	s_or_b64 exec, exec, s[48:49]
	v_cmp_lt_i32_e32 vcc, v75, v77
	s_and_b64 s[0:1], s[6:7], vcc
	s_and_saveexec_b64 s[20:21], s[0:1]
	s_cbranch_execz .LBB0_767
	v_add_u32_e32 v0, 8, v75
	v_cmp_lt_i32_e32 vcc, -1, v76
	s_and_saveexec_b64 s[0:1], vcc
	s_xor_b64 s[0:1], exec, s[0:1]
	s_cbranch_execz .LBB0_778
	v_lshl_add_u32 v0, v0, 5, v98
	v_cmp_lt_i32_e64 s[24:25], v0, v212
	v_lshrrev_b32_e32 v148, 2, v248
	v_and_b32_e32 v88, 3, v248
.LBB0_778:
	s_andn2_saveexec_b64 s[0:1], s[0:1]
	v_lshl_add_u32 v0, v0, 5, v145
	v_or_b32_e32 v148, v0, v97
	v_mov_b64_e32 v[88:89], 3
	s_or_b64 s[24:25], s[24:25], exec
	s_or_b64 exec, exec, s[0:1]
	v_lshlrev_b32_e32 v0, 10, v74
	v_and_b32_e32 v0, 0xffffe000, v0
	v_add_u32_e32 v90, v148, v0
	v_bfe_u32 v89, v66, 5, 3
	v_ashrrev_i32_e32 v91, 31, v90
	v_cmp_lt_i32_e32 vcc, -9, v75
	v_mov_b32_e32 v147, 0xf149f2ca
	v_mov_b32_e32 v31, 0
	v_mov_b32_e32 v30, 0
	v_mov_b32_e32 v29, 0
	v_mov_b32_e32 v28, 0
	v_mov_b32_e32 v27, 0
	v_mov_b32_e32 v26, 0
	v_mov_b32_e32 v25, 0
	v_mov_b32_e32 v24, 0
	v_mov_b32_e32 v23, 0
	v_mov_b32_e32 v22, 0
	v_mov_b32_e32 v21, 0
	v_mov_b32_e32 v20, 0
	v_mov_b32_e32 v19, 0
	v_mov_b32_e32 v18, 0
	v_mov_b32_e32 v17, 0
	v_mov_b32_e32 v16, 0
	v_mov_b32_e32 v47, 0
	v_mov_b32_e32 v46, 0
	v_mov_b32_e32 v45, 0
	v_mov_b32_e32 v44, 0
	v_mov_b32_e32 v43, 0
	v_mov_b32_e32 v42, 0
	v_mov_b32_e32 v41, 0
	v_mov_b32_e32 v40, 0
	v_mov_b32_e32 v39, 0
	v_mov_b32_e32 v38, 0
	v_mov_b32_e32 v37, 0
	v_mov_b32_e32 v36, 0
	v_mov_b32_e32 v35, 0
	v_mov_b32_e32 v34, 0
	v_mov_b32_e32 v33, 0
	v_mov_b32_e32 v32, 0
	v_mov_b32_e32 v4, 0
	s_and_saveexec_b64 s[48:49], vcc
	s_cbranch_execz .LBB0_795
	v_lshl_add_u32 v0, v144, 3, v142
	v_lshlrev_b32_e32 v2, 3, v146
	v_sub_u32_e32 v144, v0, v2
	v_min_u32_e32 v0, 7, v144
	v_mov_b32_e32 v14, v1
	v_mov_b32_e32 v15, v1
	v_lshl_add_u32 v146, v0, 5, 32
	v_mov_b32_e32 v0, v1
	v_mov_b32_e32 v2, v1
	v_mov_b32_e32 v3, v1
	v_mov_b32_e32 v4, v1
	v_mov_b32_e32 v5, v1
	v_mov_b32_e32 v6, v1
	v_mov_b32_e32 v7, v1
	v_mov_b32_e32 v8, v1
	v_mov_b32_e32 v9, v1
	v_mov_b32_e32 v10, v1
	v_mov_b32_e32 v11, v1
	v_mov_b32_e32 v12, v1
	v_mov_b32_e32 v13, v1
	v_mov_b64_e32 v[30:31], v[14:15]
	v_mov_b64_e32 v[46:47], v[14:15]
	v_add_u32_e32 v145, v99, v145
	s_mov_b32 s8, 0
	v_mov_b32_e32 v155, 0
	v_mov_b32_e32 v147, 0xf149f2ca
	s_mov_b64 s[50:51], 0
	v_mov_b32_e32 v149, v139
	v_mov_b32_e32 v150, v138
	v_mov_b32_e32 v151, v137
	v_mov_b32_e32 v152, v136
	v_mov_b32_e32 v153, v134
	v_mov_b32_e32 v154, v85
	v_mov_b64_e32 v[28:29], v[12:13]
	v_mov_b64_e32 v[26:27], v[10:11]
	v_mov_b64_e32 v[24:25], v[8:9]
	v_mov_b64_e32 v[22:23], v[6:7]
	v_mov_b64_e32 v[20:21], v[4:5]
	v_mov_b64_e32 v[18:19], v[2:3]
	v_mov_b64_e32 v[16:17], v[0:1]
	v_mov_b64_e32 v[44:45], v[12:13]
	v_mov_b64_e32 v[42:43], v[10:11]
	v_mov_b64_e32 v[40:41], v[8:9]
	v_mov_b64_e32 v[38:39], v[6:7]
	v_mov_b64_e32 v[36:37], v[4:5]
	v_mov_b64_e32 v[34:35], v[2:3]
	v_mov_b64_e32 v[32:33], v[0:1]
	s_branch .LBB0_783

; DI int crow(int i, int hh) { return (i & 3) + 8 * (i >> 2) + 4 * hh; }
; DI void attn_task(const Params& P, int bh, int n, int t, int lane, const char* Ks, const char* Vs) {
;     ...
;   for (int kt = 0; kt < nkt; ++kt) {
;     const int kbase = n * 256 + kt * 32;
;     const int krow = kt * 32 + r;
;     f32x16 S;
; #pragma unroll
;     for (int i = 0; i < 16; ++i) S[i] = 0.f;
; #pragma unroll
;     for (int s = 0; s < 4; ++s) {
;       const bf16x8 kf = *reinterpret_cast<const bf16x8*>(Ks + krow * 128 + (((2 * s + hh) ^ ((krow >> 1) & 7)) * 16));
;       S = __builtin_amdgcn_mfma_f32_32x32x16_bf16(kf, qf[s], S, 0, 0, 0);
;     }
;     const bool diag = own && (kt == t);
;     constexpr float SC2 = 0.125f * 1.4426950408889634f;
;     float mx = -1e30f;
; #pragma unroll
;     for (int i = 0; i < 16; ++i) {
;       if (diag && (kbase + crow(i, hh) > lq)) S[i] = -1e30f;
;       mx = fmaxf(mx, S[i]);
;     }
.LBB0_783:
	v_add_u32_e32 v0, v152, v197
	ds_read_b128 v[2:5], v0
	v_add_u32_e32 v0, v151, v197
	ds_read_b128 v[6:9], v0
	v_add_u32_e32 v10, v149, v197
	v_add_u32_e32 v11, s8, v145
	v_subrev_co_u32_e32 v144, vcc, 1, v144
	v_cmp_gt_i32_e64 s[0:1], v11, v148
	v_cmp_ge_i32_e64 s[6:7], v11, v148
	s_cbranch_vccz .Lattn_fast_783
	s_waitcnt lgkmcnt(1)
	v_mfma_f32_32x32x16_bf16 v[48:63], v[2:5], v[232:235], 0
	v_add_u32_e32 v2, v150, v197
	ds_read_b128 v[2:5], v2
	s_and_b64 s[0:1], vcc, s[0:1]
	v_add_u32_e32 v12, 3, v11
	v_add_u32_e32 v13, 8, v11
	v_cmp_gt_i32_e64 s[12:13], v12, v148
	v_add_u32_e32 v14, 9, v11
	s_waitcnt lgkmcnt(1)
	v_mfma_f32_32x32x16_bf16 v[48:63], v[6:9], v[236:239], v[48:63]
	ds_read_b128 v[6:9], v10
	v_add_u32_e32 v210, v153, v197
	v_add_u32_e32 v211, v154, v197
	ds_read2_b64 v[216:219], v210 offset1:2
	ds_read2_b64 v[220:223], v211 offset1:2
	ds_read2_b64 v[224:227], v210 offset0:4 offset1:6
	ds_read2_b64 v[228:231], v211 offset0:4 offset1:6
	v_add_u32_e32 v10, 2, v11
	v_cmp_gt_i32_e64 s[10:11], v10, v148
	v_cmp_gt_i32_e64 s[14:15], v13, v148
	v_cmp_gt_i32_e64 s[16:17], v14, v148
	v_mov_b32_e32 v0, v147
	s_waitcnt lgkmcnt(5)
	v_mfma_f32_32x32x16_bf16 v[48:63], v[2:5], v[240:243], v[48:63]
	v_add_u32_e32 v2, 10, v11
	v_cmp_gt_i32_e64 s[18:19], v2, v148
	v_add_u32_e32 v3, 11, v11
	s_waitcnt lgkmcnt(4)
	v_mfma_f32_32x32x16_bf16 v[48:63], v[6:9], v[244:247], v[48:63]
	v_add_u32_e32 v6, 16, v11
	s_nop 10
	v_cndmask_b32_e64 v2, v48, v143, s[0:1]
	s_and_b64 s[0:1], vcc, s[6:7]
	v_cndmask_b32_e64 v5, v49, v143, s[0:1]
	s_and_b64 s[0:1], vcc, s[10:11]
	v_cndmask_b32_e64 v7, v50, v143, s[0:1]
	s_and_b64 s[0:1], vcc, s[12:13]
	v_cndmask_b32_e64 v9, v51, v143, s[0:1]
	s_and_b64 s[0:1], vcc, s[14:15]
	v_cndmask_b32_e64 v10, v52, v143, s[0:1]
	s_and_b64 s[0:1], vcc, s[16:17]
	v_cndmask_b32_e64 v13, v53, v143, s[0:1]
	s_and_b64 s[0:1], vcc, s[18:19]
	v_cndmask_b32_e64 v15, v54, v143, s[0:1]
	v_cmp_gt_i32_e64 s[0:1], v3, v148
	s_and_b64 s[0:1], vcc, s[0:1]
	v_max3_f32 v4, v2, s22, v5
	v_cndmask_b32_e64 v3, v55, v143, s[0:1]
	v_cmp_gt_i32_e64 s[0:1], v6, v148
	s_and_b64 s[0:1], vcc, s[0:1]
	v_add_u32_e32 v6, 17, v11
	v_cndmask_b32_e64 v50, v56, v143, s[0:1]
	v_cmp_gt_i32_e64 s[0:1], v6, v148
	s_and_b64 s[0:1], vcc, s[0:1]
	v_add_u32_e32 v6, 18, v11
	v_cndmask_b32_e64 v51, v57, v143, s[0:1]
	v_cmp_gt_i32_e64 s[0:1], v6, v148
	s_and_b64 s[0:1], vcc, s[0:1]
	v_add_u32_e32 v6, 19, v11
	v_cndmask_b32_e64 v52, v58, v143, s[0:1]
	v_cmp_gt_i32_e64 s[0:1], v6, v148
	s_and_b64 s[0:1], vcc, s[0:1]
	v_add_u32_e32 v6, 24, v11
	v_cndmask_b32_e64 v53, v59, v143, s[0:1]
	v_cmp_gt_i32_e64 s[0:1], v6, v148
	s_and_b64 s[0:1], vcc, s[0:1]
	v_add_u32_e32 v6, 25, v11
	v_cndmask_b32_e64 v54, v60, v143, s[0:1]
	v_cmp_gt_i32_e64 s[0:1], v6, v148
	v_max3_f32 v4, v4, v7, v9
	s_and_b64 s[0:1], vcc, s[0:1]
	v_add_u32_e32 v6, 26, v11
	v_max3_f32 v4, v4, v10, v13
	v_cndmask_b32_e64 v55, v61, v143, s[0:1]
	v_cmp_gt_i32_e64 s[0:1], v6, v148
	v_max3_f32 v4, v4, v15, v3
	s_and_b64 s[0:1], vcc, s[0:1]
	v_add_u32_e32 v6, 27, v11
	v_max3_f32 v4, v4, v50, v51
	v_cndmask_b32_e64 v56, v62, v143, s[0:1]
	v_cmp_gt_i32_e64 s[0:1], v6, v148
	v_max3_f32 v4, v4, v52, v53
	s_and_b64 vcc, vcc, s[0:1]
	v_max3_f32 v4, v4, v54, v55
	v_cndmask_b32_e32 v57, v63, v143, vcc
	v_max3_f32 v4, v4, v56, v57

; DI void attn_task(const Params& P, int bh, int n, int t, int lane, const char* Ks, const char* Vs) {
;     ...
;   int lq, slot; bool valid = true;
;   if (own) { lq = n * 256 + t * 32 + r; slot = 3; }
;   else {
;     const int cnt = gcount[bh * 32 + n], idx = (t - 8) * 32 + r;
;     valid = idx < cnt;
;     const int e = list[((long)(bh * 32 + n)) * 8192 + (valid ? idx : 0)];
;     lq = e >> 2; slot = e & 3;
;   }
;   bf16x8 qf[4];
;   {
;     const u16* qrow = Qb + ((long)(b * 8192 + lq)) * 512 + h * 64 + 8 * hh;
; #pragma unroll
;     for (int s = 0; s < 4; ++s) qf[s] = *reinterpret_cast<const bf16x8*>(qrow + 16 * s);
;   }
;   float m_run = -1e30f, l_run = 0.f;
;   f32x16 O0, O1;
; #pragma unroll
;   for (int i = 0; i < 16; ++i) { O0[i] = 0.f; O1[i] = 0.f; }
;   const int nkt = own ? (t + 1) : 8;
.LBB0_785:
	v_or_b32_e32 v0, 4, v75
	v_cmp_ne_u32_e32 vcc, v144, v146
	s_and_saveexec_b64 s[0:1], vcc
	s_xor_b64 s[0:1], exec, s[0:1]
	s_cbranch_execz .LBB0_787
	v_lshl_add_u32 v0, v0, 5, v98
	v_cmp_lt_i32_e64 s[50:51], v0, v212
	v_lshrrev_b32_e32 v78, 2, v249
	v_and_b32_e32 v70, 3, v249
.LBB0_787:
	s_andn2_saveexec_b64 s[0:1], s[0:1]
	v_lshl_add_u32 v0, v0, 5, v145
	v_or_b32_e32 v78, v0, v97
	v_mov_b64_e32 v[70:71], 3
	s_or_b64 s[50:51], s[50:51], exec
	s_or_b64 exec, exec, s[0:1]
	v_lshlrev_b32_e32 v0, 10, v74
	v_and_b32_e32 v0, 0xffffe000, v0
	v_add_u32_e32 v72, v78, v0
	v_ashrrev_i32_e32 v73, 31, v72
	v_bfe_u32 v79, v66, 5, 3
	v_lshl_or_b32 v0, v144, 3, v135
	v_lshlrev_b32_e32 v2, 3, v146
	v_mov_b32_e32 v14, v1
	v_mov_b32_e32 v15, v1
	v_sub_u32_e32 v88, v0, v2
	v_mov_b32_e32 v0, v1
	v_mov_b32_e32 v2, v1
	v_mov_b32_e32 v3, v1
	v_mov_b32_e32 v4, v1
	v_mov_b32_e32 v5, v1
	v_mov_b32_e32 v6, v1
	v_mov_b32_e32 v7, v1
	v_mov_b32_e32 v8, v1
	v_mov_b32_e32 v9, v1
	v_mov_b32_e32 v10, v1
	v_mov_b32_e32 v11, v1
	v_mov_b32_e32 v12, v1
	v_mov_b32_e32 v13, v1
	v_mov_b64_e32 v[32:33], v[14:15]
	v_mov_b64_e32 v[30:31], v[12:13]
	v_mov_b64_e32 v[28:29], v[10:11]
	v_mov_b64_e32 v[26:27], v[8:9]
	v_mov_b64_e32 v[24:25], v[6:7]
	v_mov_b64_e32 v[22:23], v[4:5]
	v_mov_b64_e32 v[20:21], v[2:3]
	v_mov_b64_e32 v[18:19], v[0:1]
	v_mov_b64_e32 v[16:17], v[14:15]
	v_add_u32_e32 v89, v99, v145
	s_mov_b32 s8, 0
	v_mov_b32_e32 v151, 0
	v_mov_b32_e32 v71, 0xf149f2ca
	v_mov_b32_e32 v90, v139
	v_mov_b32_e32 v91, v138
	v_mov_b32_e32 v147, v137
	v_mov_b32_e32 v148, v136
	v_mov_b32_e32 v149, v134
	v_mov_b32_e32 v150, v85
	v_mov_b64_e32 v[14:15], v[12:13]
	v_mov_b64_e32 v[12:13], v[10:11]
	v_mov_b64_e32 v[10:11], v[8:9]
	v_mov_b64_e32 v[8:9], v[6:7]
	v_mov_b64_e32 v[6:7], v[4:5]
	v_mov_b64_e32 v[4:5], v[2:3]
	v_mov_b64_e32 v[2:3], v[0:1]

; DI int crow(int i, int hh) { return (i & 3) + 8 * (i >> 2) + 4 * hh; }
; DI void attn_task(const Params& P, int bh, int n, int t, int lane, const char* Ks, const char* Vs) {
;     ...
; #pragma unroll
;     for (int s = 0; s < 4; ++s) {
;       const bf16x8 kf = *reinterpret_cast<const bf16x8*>(Ks + krow * 128 + (((2 * s + hh) ^ ((krow >> 1) & 7)) * 16));
;       S = __builtin_amdgcn_mfma_f32_32x32x16_bf16(kf, qf[s], S, 0, 0, 0);
;     }
;     const bool diag = own && (kt == t);
;     constexpr float SC2 = 0.125f * 1.4426950408889634f;
;     float mx = -1e30f;
; #pragma unroll
;     for (int i = 0; i < 16; ++i) {
;       if (diag && (kbase + crow(i, hh) > lq)) S[i] = -1e30f;
;       mx = fmaxf(mx, S[i]);
;     }
.Lattn_fast_783:
	s_waitcnt lgkmcnt(1)
	v_mfma_f32_32x32x16_bf16 v[48:63], v[2:5], v[232:235], 0
	v_add_u32_e32 v2, v150, v197
	ds_read_b128 v[2:5], v2
	s_waitcnt lgkmcnt(1)
	v_mfma_f32_32x32x16_bf16 v[48:63], v[6:9], v[236:239], v[48:63]
	ds_read_b128 v[6:9], v10
	v_add_u32_e32 v210, v153, v197
	v_add_u32_e32 v211, v154, v197
	ds_read2_b64 v[216:219], v210 offset1:2
	ds_read2_b64 v[220:223], v211 offset1:2
	ds_read2_b64 v[224:227], v210 offset0:4 offset1:6
	ds_read2_b64 v[228:231], v211 offset0:4 offset1:6
	v_mov_b32_e32 v0, v147
	s_waitcnt lgkmcnt(5)
	v_mfma_f32_32x32x16_bf16 v[48:63], v[2:5], v[240:243], v[48:63]
	s_waitcnt lgkmcnt(4)
	v_mfma_f32_32x32x16_bf16 v[48:63], v[6:9], v[244:247], v[48:63]
	s_nop 11
	v_mov_b32_e32 v2, v48
	v_mov_b32_e32 v5, v49
	v_mov_b32_e32 v7, v50
	v_mov_b32_e32 v9, v51
	v_mov_b32_e32 v10, v52
	v_mov_b32_e32 v13, v53
	v_mov_b32_e32 v15, v54
	v_mov_b32_e32 v3, v55
	v_mov_b32_e32 v50, v56
	v_mov_b32_e32 v51, v57
	v_mov_b32_e32 v52, v58
	v_mov_b32_e32 v53, v59
	v_mov_b32_e32 v54, v60
	v_mov_b32_e32 v55, v61
	v_mov_b32_e32 v56, v62
	v_mov_b32_e32 v57, v63
	v_max3_f32 v4, v2, s22, v5
	v_max3_f32 v4, v4, v7, v9
	v_max3_f32 v4, v4, v10, v13
	v_max3_f32 v4, v4, v15, v3
	v_max3_f32 v4, v4, v50, v51
	v_max3_f32 v4, v4, v52, v53
	v_max3_f32 v4, v4, v54, v55
	v_max3_f32 v4, v4, v56, v57
	s_branch .Lattn_join_783
